# context rows owned per XCD: residual ctx tiles remapped to the XCD's own batches; arrival counters B/E per XCD and C/D per XCD pair (no deliberate offset)
# speedup vs baseline: 1.0040x; 1.0029x over previous
; DI void grid_barrier(unsigned* cnt, unsigned target) {
;     asm volatile("s_waitcnt vmcnt(0) lgkmcnt(0)" ::: "memory");
;     __syncthreads();
;     if (threadIdx.x == 0) {
;         __builtin_amdgcn_fence(__ATOMIC_RELEASE, "agent");
;         asm volatile("s_waitcnt vmcnt(0)" ::: "memory");
;         __hip_atomic_fetch_add(cnt, 1u, __ATOMIC_RELAXED, __HIP_MEMORY_SCOPE_AGENT);
;         while (__hip_atomic_load(cnt, __ATOMIC_RELAXED, __HIP_MEMORY_SCOPE_AGENT) < target) __builtin_amdgcn_s_sleep(2);
;         __builtin_amdgcn_fence(__ATOMIC_ACQUIRE, "agent");
;         asm volatile("s_waitcnt vmcnt(0)" ::: "memory");
;     }
;     __syncthreads();
; }
.Lres_go:
	s_cmp_eq_u32 s98, 1
	s_cbranch_scc0 .Lres_nowd
	v_readlane_b32 s33, v255, 62
	s_lshl_b32 s33, s33, 6
	s_mov_b64 s[30:31], exec
	v_readlane_b32 s40, v255, 3
	v_readlane_b32 s41, v255, 4
	s_and_b64 s[40:41], s[30:31], s[40:41]
	s_mov_b64 exec, s[40:41]
	s_cbranch_execz .Lwd_D
	s_bfe_u32 s40, s2, 0x20001
	s_lshl_b32 s40, s40, 2
	s_add_u32 s40, s14, s40
	s_addc_u32 s41, s15, 0
.Lwp_D:
	global_load_dword v0, v1, s[40:41] offset:176 sc1
	s_waitcnt vmcnt(0)
	v_cmp_gt_u32_e32 vcc, s33, v0
	s_cbranch_vccz .Lwi_D
	s_sleep 2
	s_branch .Lwp_D

; DI void grid_barrier(unsigned* cnt, unsigned target) {
;     asm volatile("s_waitcnt vmcnt(0) lgkmcnt(0)" ::: "memory");
;     __syncthreads();
;     if (threadIdx.x == 0) {
;         __builtin_amdgcn_fence(__ATOMIC_RELEASE, "agent");
;         asm volatile("s_waitcnt vmcnt(0)" ::: "memory");
;         __hip_atomic_fetch_add(cnt, 1u, __ATOMIC_RELAXED, __HIP_MEMORY_SCOPE_AGENT);
;         while (__hip_atomic_load(cnt, __ATOMIC_RELAXED, __HIP_MEMORY_SCOPE_AGENT) < target) __builtin_amdgcn_s_sleep(2);
;         __builtin_amdgcn_fence(__ATOMIC_ACQUIRE, "agent");
;         asm volatile("s_waitcnt vmcnt(0)" ::: "memory");
;     }
;     __syncthreads();
; }
.Lwd_D:
	s_mov_b64 exec, s[30:31]
	s_barrier
	s_cmp_eq_u32 s44, 10
	s_cbranch_scc0 .Lres_nowd
	v_readlane_b32 s33, v255, 63
	s_lshl_b32 s33, s33, 5
	s_mov_b64 s[30:31], exec
	v_readlane_b32 s40, v255, 3
	v_readlane_b32 s41, v255, 4
	s_and_b64 s[40:41], s[30:31], s[40:41]
	s_mov_b64 exec, s[40:41]
	s_cbranch_execz .Lwd_E
	s_and_b32 s40, s2, 7
	s_lshl_b32 s40, s40, 2
	s_add_u32 s40, s14, s40
	s_addc_u32 s41, s15, 0
.Lwp_E:
	global_load_dword v0, v1, s[40:41] offset:208 sc1
	s_waitcnt vmcnt(0)
	v_cmp_gt_u32_e32 vcc, s33, v0
	s_cbranch_vccz .Lwi_E
	s_sleep 2
	s_branch .Lwp_E

;     DI bool next(int i, Unit& u) const {
;     ...
;         int wgid = (int)L; { const int q = nwg / NXCD, r = nwg % NXCD, xcd = wgid % NXCD, off = wgid / NXCD; wgid = (xcd < r ? xcd * (q + 1) : r * (q + 1) + (xcd - r) * q) + off; }
;         u.pz = wgid / per; const int w = wgid % per;
;         const int nig = WGM * nN, gid = w / nig, fm = gid * WGM, gsz = (nM - fm) < WGM ? (nM - fm) : WGM;
;         u.pm = pm0 + fm + ((w % nig) % gsz); u.pn = (w % nig) / gsz; return true;
; template <class Epi>
; DI void gemm_phase(LAS unsigned char* lds, int tid, const Gemm g, const Order& S, const Epi& E) {
;     const int wid = __builtin_amdgcn_readfirstlane(tid >> 6), lane = tid & 63, wr = wid >> 2, wc = wid & 3, fr = lane & 15, fq = lane >> 4;
;     const int K = g.K, nt = K / BK;
;     unsigned voffA[2], voffB[2];
; #pragma unroll
;     for (int i = 0; i < 2; ++i) { int R, C; stage_rc(tid * 16 + i * 8192, R, C); const int Rb = (R & ~31) + perm32(R & 31);
;         voffA[i] = (unsigned)(R * g.lda + C) * 2u; voffB[i] = (unsigned)(Rb * g.ldb + C) * 2u; }
;     const size_t kstep = (size_t)(BK * 2);
;     const size_t hstepA = (size_t)HALF * g.lda * 2, hstepB = (size_t)HALF * g.ldb * 2;
;     const unsigned ldsw = (unsigned)wid * 1024u;
;     const int aoff = lds_byte(wr * 64 + fr, fq * 8), boff = lds_byte(wc * 32 + fr, fq * 8);
.Lres_nowd:
	v_lshlrev_b32_e32 v0, 4, v164
	v_add_u32_e32 v2, 0x2000, v0
	v_ashrrev_i32_e32 v3, 31, v2
	v_lshrrev_b32_e32 v3, 22, v3
	v_add_u32_e32 v3, v2, v3
	v_ashrrev_i32_e32 v3, 10, v3
	v_mul_i32_i24_e32 v4, 0x400, v3
	v_sub_u32_e32 v2, v2, v4
	v_lshrrev_b32_e32 v4, 4, v2
	v_bitop3_b32 v2, v4, v2, 32 bitop3:0x6c
	v_ashrrev_i32_e32 v4, 31, v2
	v_lshrrev_b32_e32 v4, 26, v4
	v_add_u32_e32 v4, v2, v4
	v_lshlrev_b32_e32 v6, 3, v3
	v_ashrrev_i32_e32 v5, 6, v4
	v_and_b32_e32 v6, -16, v6
	v_lshlrev_b32_e32 v3, 5, v3
	v_add_u32_e32 v6, v5, v6
	v_and_b32_e32 v14, 32, v3
	v_and_b32_e32 v3, 0xc0, v4
	v_and_b32_e32 v5, 3, v5
	s_mov_b32 s4, 0x7fffffe0
	v_lshrrev_b32_e32 v7, 2, v6
	v_lshlrev_b32_e32 v8, 1, v6
	v_sub_u32_e32 v2, v2, v3
	v_and_or_b32 v5, v6, s4, v5
	v_and_b32_e32 v7, 4, v7
	v_and_b32_e32 v8, 24, v8
	v_ashrrev_i16_sdwa v2, v193, sext(v2) dst_sel:DWORD dst_unused:UNUSED_PAD src0_sel:DWORD src1_sel:BYTE_0
	v_or3_b32 v5, v5, v7, v8
	v_bfe_i32 v15, v2, 0, 16
	v_mul_lo_u32 v5, s6, v5
	v_add_u32_e32 v2, v14, v15
	v_mul_lo_u32 v16, s6, v6
	v_add_lshl_u32 v130, v5, v2, 1
	v_add_lshl_u32 v132, v16, v2, 1
	v_bfe_i32 v2, v164, 27, 1
	v_lshrrev_b32_e32 v2, 22, v2
	v_add_u32_e32 v2, v0, v2
	v_and_b32_e32 v2, 0xfffffc00, v2
	v_sub_u32_e32 v0, v0, v2
	v_lshrrev_b32_e32 v2, 4, v0
	v_ashrrev_i32_e32 v4, 31, v164
	v_bitop3_b32 v0, v2, v0, 32 bitop3:0x6c
	v_lshrrev_b32_e32 v4, 26, v4
	v_ashrrev_i32_e32 v2, 31, v0
	v_add_u32_e32 v4, v164, v4
	v_lshrrev_b32_e32 v2, 26, v2
	v_ashrrev_i32_e32 v4, 6, v4
	v_add_u32_e32 v2, v0, v2
	v_lshlrev_b32_e32 v5, 3, v4
	v_ashrrev_i32_e32 v3, 6, v2
	v_and_b32_e32 v5, -16, v5
	v_add_u32_e32 v5, v3, v5
	v_and_b32_e32 v2, 0xc0, v2
	v_and_b32_e32 v3, 3, v3
	v_lshrrev_b32_e32 v6, 2, v5
	v_lshlrev_b32_e32 v7, 1, v5
	v_sub_u32_e32 v0, v0, v2
	v_and_or_b32 v3, v5, s4, v3
	v_and_b32_e32 v6, 4, v6
	v_and_b32_e32 v7, 24, v7
	v_lshlrev_b32_e32 v4, 5, v4
	v_ashrrev_i16_sdwa v0, v193, sext(v0) dst_sel:DWORD dst_unused:UNUSED_PAD src0_sel:DWORD src1_sel:BYTE_0
	v_or3_b32 v3, v3, v6, v7
	v_and_b32_e32 v17, 32, v4
	v_bfe_i32 v18, v0, 0, 16
	v_mul_lo_u32 v3, s6, v3
	v_add_u32_e32 v2, v17, v18
	v_mul_lo_u32 v19, s6, v5
	v_add_lshl_u32 v0, v3, v2, 1
	v_add_lshl_u32 v134, v19, v2, 1
	v_cvt_f32_u32_e32 v2, s74
	s_ashr_i32 s34, s2, 31
	s_lshr_b32 s4, s34, 29
	s_add_i32 s4, s2, s4
	v_rcp_iflag_f32_e32 v2, v2
	s_ashr_i32 s17, s4, 3
	s_and_b32 s4, s4, -8
	s_sub_i32 s4, s2, s4
	v_mul_f32_e32 v2, 0x4f7ffffe, v2
	v_cvt_u32_f32_e32 v2, v2
	s_lshr_b32 s11, s42, 1
	s_lshr_b32 s18, s4, 31
	s_or_b32 s18, s11, s18
	s_mul_i32 s4, s4, s18
	s_sub_i32 s18, 0, s74
	v_readfirstlane_b32 s43, v2
	s_mul_i32 s18, s18, s43
	s_add_i32 s4, s4, s17
	s_mul_hi_u32 s18, s43, s18
	s_ashr_i32 s17, s4, 31
	s_abs_i32 s4, s4
	s_add_i32 s43, s43, s18
	s_mul_hi_u32 s18, s4, s43
	s_mul_i32 s18, s18, s74
	s_ashr_i32 s7, s5, 6
	s_sub_i32 s4, s4, s18
	s_ashr_i32 s16, s5, 8
	s_lshl_b32 s20, s6, 8
	s_lshl_b32 s10, s7, 10
	s_sub_i32 s18, s4, s74
	s_cmp_ge_u32 s4, s74
	s_cselect_b32 s4, s18, s4
	s_sub_i32 s18, s4, s74
	s_cmp_ge_u32 s4, s74
	s_cselect_b32 s4, s18, s4
	s_xor_b32 s4, s4, s17
	s_sub_i32 s4, s4, s17
	s_sext_i32_i16 s17, s4
	s_bfe_u32 s17, s17, 0x4001b
	s_add_i32 s17, s4, s17
	s_sext_i32_i16 s18, s17
	s_ashr_i32 s18, s18, 4
	s_lshl_b32 s22, s18, 2
	s_sub_i32 s18, s42, s22
	s_min_i32 s26, s18, 4
	s_sext_i32_i8 s18, s26
	v_cvt_f32_i32_e32 v3, s18
	s_and_b32 s17, s17, 0xfff0
	s_sub_i32 s17, s4, s17
	s_sext_i32_i16 s4, s17
	v_cvt_f32_i32_e32 v2, s4
	v_rcp_iflag_f32_e32 v4, v3
	s_xor_b32 s19, s4, s18
	s_ashr_i32 s19, s19, 30
	s_or_b32 s28, s19, 1
	v_mul_f32_e32 v4, v2, v4
	v_trunc_f32_e32 v4, v4
	v_fma_f32 v2, -v4, v3, v2
	v_cvt_i32_f32_e32 v4, v4
	v_cmp_ge_f32_e64 s[18:19], |v2|, |v3|
	s_and_b64 s[18:19], s[18:19], exec
	s_cselect_b32 s4, s28, 0
	v_readfirstlane_b32 s18, v4
	s_add_i32 s4, s18, s4
	s_mul_i32 s18, s4, s26
	s_sub_i32 s17, s17, s18
	s_cmp_eq_u32 s98, 1
	s_cbranch_scc0 .Lres_noctx
	s_lshr_b32 s4, s2, 3
	s_and_b32 s4, s4, 3
	s_lshr_b32 s17, s2, 5
	s_and_b32 s22, s2, 7
	s_lshl_b32 s22, s22, 1
	s_add_u32 s22, s22, s17
	s_addk_i32 s22, 0x100
	s_mov_b32 s17, 0
	s_mov_b32 s74, 0

; DI void norm_phase(Frame& F, const float* srcL, const float* srcC, const float* g, const float* modl, int sub) {
;     const int gw = F.vcu * 8 + F.wave; constexpr int RPW = TT / 2048;
;     bf16_t* H = WSP(bf16_t, WS_H);
;     int cur_bi = -1; f32x4 gs[4], sh[4];
;     for (int row = gw * RPW; row < gw * RPW + RPW; ++row) {
;         const int bi = row < TL ? (row >> 12) : 16;
;         if (bi != cur_bi) { cur_bi = bi; const float* mp = modl + (size_t)bi * MODW + sub * 3072;
; #pragma unroll
;             for (int j = 0; j < 4; ++j) { const int k = (F.lane + 64 * j) * 4; const f32x4 gg = *(const f32x4*)(g + k), sc = *(const f32x4*)(mp + 1024 + k); sh[j] = *(const f32x4*)(mp + k); gs[j] = gg * (sc + 1.0f); } }
.LBB0_522:
	s_andn2_b64 vcc, exec, s[4:5]
	s_cbranch_vccnz .LBB0_578
	s_cmp_lg_u32 s35, 1
	s_cbranch_scc1 .LBB0_578
	s_cmp_eq_u32 s44, 3
	v_readlane_b32 s6, v255, 17
	s_cselect_b64 s[4:5], -1, 0
	v_readlane_b32 s7, v255, 18
	s_and_b64 s[6:7], s[6:7], s[4:5]
	s_andn2_b64 vcc, exec, s[6:7]
	s_mov_b64 s[6:7], -1
	v_readlane_b32 s12, v255, 28
	s_cbranch_vccz .LBB0_532
	s_and_b64 s[4:5], s[4:5], exec
	s_cselect_b32 s2, 1, 2
	s_cmp_lg_u32 s44, 0
	s_mov_b32 s4, 4
	s_cselect_b32 s2, s2, 0
	s_ashr_i32 s5, s4, 31
	s_lshl_b64 s[4:5], s[4:5], 3
	s_add_u32 s4, s0, s4
	s_mul_i32 s6, s36, 3
	s_addc_u32 s5, s1, s5
	s_add_i32 s6, s2, s6
	v_cmp_lt_i32_e32 vcc, v181, v180
	s_lshl_b32 s20, s6, 10
	s_load_dwordx2 s[4:5], s[4:5], 0x0
	v_cndmask_b32_e32 v0, v169, v181, vcc
	v_cmp_lt_i32_e32 vcc, v182, v180
	s_lshl_b64 s[6:7], s[20:21], 2
	v_lshlrev_b32_e32 v35, 2, v0
	v_cndmask_b32_e32 v0, v169, v182, vcc
	v_cmp_lt_i32_e32 vcc, v183, v180
	s_waitcnt lgkmcnt(0)
	s_add_u32 s6, s4, s6
	v_lshlrev_b32_e32 v40, 2, v0
	v_cndmask_b32_e32 v0, v169, v183, vcc
	v_cmp_lt_i32_e32 vcc, v192, v180
	s_addc_u32 s7, s5, s7
	s_lshl_b32 s4, s12, 3
	v_lshlrev_b32_e32 v41, 2, v0
	v_cndmask_b32_e32 v0, v169, v192, vcc
	v_cmp_lt_i32_e32 vcc, v254, v180
	s_add_i32 s4, s4, s50
	v_lshlrev_b32_e32 v42, 2, v0
	v_cndmask_b32_e32 v0, v169, v254, vcc
	v_cmp_lt_i32_e32 vcc, v186, v180
	s_mulk_i32 s2, 0x3000
	s_mul_i32 s4, s4, 34
	v_lshlrev_b32_e32 v43, 2, v0
	v_cndmask_b32_e32 v0, v169, v186, vcc
	s_add_u32 s2, s29, s2
	v_lshlrev_b32_e32 v44, 2, v0
	s_addc_u32 s10, s94, 0
	v_lshlrev_b32_e32 v0, 4, v194
	s_ashr_i32 s5, s4, 31
	s_add_i32 s11, s4, 33
	v_lshlrev_b32_e32 v34, 2, v194
	v_lshl_add_u64 v[36:37], s[6:7], 0, v[0:1]
	s_lshl_b64 s[6:7], s[4:5], 12
	v_or_b32_e32 v16, 0x100, v34
	v_lshlrev_b32_e32 v0, 3, v194
	s_add_u32 s6, s54, s6
	s_mul_i32 s8, s12, 0x110
	s_mul_i32 s9, s50, 34
	v_mov_b32_e32 v2, v1
	v_mov_b32_e32 v3, v1
	v_mov_b32_e32 v4, v1
	v_mov_b32_e32 v5, v1
	v_mov_b32_e32 v6, v1
	v_mov_b32_e32 v7, v1
	v_mov_b32_e32 v8, v1
	v_mov_b32_e32 v9, v1
	v_mov_b32_e32 v10, v1
	v_mov_b32_e32 v11, v1
	v_mov_b32_e32 v12, v1
	v_mov_b32_e32 v13, v1
	v_mov_b32_e32 v14, v1
	v_mov_b32_e32 v15, v1
	v_or_b32_e32 v18, 0x200, v34
	v_or_b32_e32 v20, 0x300, v34
	v_lshl_add_u64 v[38:39], s[58:59], 0, v[0:1]
	s_addc_u32 s7, s55, s7
	s_add_i32 s8, s8, s9
	v_mov_b32_e32 v0, v1
	v_lshlrev_b32_e32 v45, 2, v16
	v_mov_b64_e32 v[16:17], v[14:15]
	s_mov_b32 s17, -1
	s_add_i32 s16, s8, -1
	v_lshlrev_b32_e32 v46, 2, v18
	v_lshlrev_b32_e32 v47, 2, v20
	v_mov_b64_e32 v[14:15], v[12:13]
	v_mov_b64_e32 v[12:13], v[10:11]
	v_mov_b64_e32 v[10:11], v[8:9]
	v_mov_b64_e32 v[8:9], v[6:7]
	v_mov_b64_e32 v[6:7], v[4:5]
	v_mov_b64_e32 v[4:5], v[2:3]
	v_mov_b64_e32 v[2:3], v[0:1]
	s_mov_b32 s101, 0
	s_cmp_eq_u32 s98, 2
	s_cbranch_scc0 .Lnp_nosplit
	s_and_b32 s99, s12, 31
	s_lshr_b32 s8, s12, 5
	s_cmp_lt_u32 s99, 8
	s_cbranch_scc0 .Lnp_classB
	s_mov_b64 s[18:19], exec
	v_readlane_b32 s30, v255, 3
	v_readlane_b32 s31, v255, 4
	s_and_b64 s[30:31], s[18:19], s[30:31]
	s_mov_b64 exec, s[30:31]
	s_cbranch_execz .Lnp_wdone_a
	s_lshl_b32 s9, s100, 3
	s_lshr_b32 s30, s12, 5
	s_lshl_b32 s30, s30, 2
	s_add_u32 s30, s14, s30
	s_addc_u32 s31, s15, 0
.Lnp_poll_a:
	global_load_dword v0, v1, s[30:31] offset:64 sc1
	s_waitcnt vmcnt(0)
	v_cmp_gt_u32_e32 vcc, s9, v0
	s_cbranch_vccz .Lnp_pdone_a
	s_sleep 2
	s_branch .Lnp_poll_a

; DI unsigned pk2(float lo, float hi) { f32x2 v = {lo, hi}; bf16x2_t b = __builtin_convertvector(v, bf16x2_t); return __builtin_bit_cast(unsigned, b); }
; DI void norm_phase(Frame& F, const float* srcL, const float* srcC, const float* g, const float* modl, int sub) {
;     ...
;     for (int row = gw * RPW; row < gw * RPW + RPW; ++row) {
;         const int bi = row < TL ? (row >> 12) : 16;
;         if (bi != cur_bi) { cur_bi = bi; const float* mp = modl + (size_t)bi * MODW + sub * 3072;
; #pragma unroll
;             for (int j = 0; j < 4; ++j) { const int k = (F.lane + 64 * j) * 4; const f32x4 gg = *(const f32x4*)(g + k), sc = *(const f32x4*)(mp + 1024 + k); sh[j] = *(const f32x4*)(mp + k); gs[j] = gg * (sc + 1.0f); } }
;         const float* src = row < TL ? srcL + (size_t)row * DM : srcC + (size_t)(row - TL) * DM;
;         f32x4 v[4]; float ss = 0.f;
; #pragma unroll
;         for (int j = 0; j < 4; ++j) { v[j] = __builtin_nontemporal_load((const f32x4*)(src + (F.lane + 64 * j) * 4)); ss += (v[j][0] * v[j][0] + v[j][1] * v[j][1]) + (v[j][2] * v[j][2] + v[j][3] * v[j][3]); }
;         const float rstd = rsqrtf(wave_sum(ss) * (1.0f / DM) + EPS);
;         bf16_t* hp = H + (size_t)row * DM;
; #pragma unroll
;         for (int j = 0; j < 4; ++j) { const f32x4 o = v[j] * rstd * gs[j] + sh[j]; u32x2 w; w.x = pk2(o[0], o[1]); w.y = pk2(o[2], o[3]); *(u32x2*)(hp + (F.lane + 64 * j) * 4) = w; }
;     }
.LBB0_531:
	s_cmp_eq_u32 s101, 1
	s_cbranch_scc0 .Lnp_fin
	s_mov_b32 s101, 0
	s_mov_b64 s[18:19], exec
	v_readlane_b32 s30, v255, 3
	v_readlane_b32 s31, v255, 4
	s_and_b64 s[30:31], s[18:19], s[30:31]
	s_mov_b64 exec, s[30:31]
	s_cbranch_execz .Lnp_wdone_b
	s_lshl_b32 s9, s100, 3
	s_lshr_b32 s30, s12, 5
	s_lshl_b32 s30, s30, 2
	s_add_u32 s30, s14, s30
	s_addc_u32 s31, s15, 0

; DI void norm_pair_phase(Frame& F, const float* srcL, const float* srcC, const float* g, const float* modl, int sub) {
;     bf16_t* H = WSP(bf16_t, WS_H); bf16_t* HS = WSP(bf16_t, WS_HS);
;     const int gw = F.vcu * 8 + F.wave, NGW = F.G * 8, lane = F.lane;
;     int cur_bi = -1; f32x4 gs[4], sh[4];
;     const int NT_L = NB * 2049, NT = NT_L + TC / 2;
;     for (int task = gw; task < NT; task += NGW) {
;         int bi, r1, r2, j; bool single, isc = task >= NT_L;
;         if (!isc) { bi = task / 2049; j = task % 2049; single = (j == 0 || j == 2048); r1 = bi * SEQ + j; r2 = single ? r1 : bi * SEQ + SEQ - j; }
;         else { bi = 16; j = 0; single = false; r1 = TL + 2 * (task - NT_L); r2 = r1 + 1; }
;         if (bi != cur_bi) { cur_bi = bi; const float* mp = modl + (size_t)bi * MODW + sub * 3072;
; #pragma unroll
;             for (int q = 0; q < 4; ++q) { const int k = (lane + 64 * q) * 4; const f32x4 gg = *(const f32x4*)(g + k), sc = *(const f32x4*)(mp + 1024 + k); sh[q] = *(const f32x4*)(mp + k); gs[q] = gg * (sc + 1.0f); } }
.LBB0_532:
	s_and_b64 vcc, exec, s[6:7]
	s_cbranch_vccz .LBB0_578
	s_mov_b32 s4, 4
	s_ashr_i32 s5, s4, 31
	s_lshl_b64 s[4:5], s[4:5], 3
	s_add_u32 s4, s0, s4
	s_addc_u32 s5, s1, s5
	s_lshl_b32 s2, s12, 3
	s_add_i32 s2, s2, s50
	s_load_dwordx2 s[4:5], s[4:5], 0x0
	s_cmp_gt_i32 s2, 0x880f
	s_waitcnt lgkmcnt(0)
	s_cbranch_scc1 .LBB0_578
	s_add_u32 s60, s60, 0x36d00000
	s_addc_u32 s61, s61, 0
	s_lshl_b32 s10, s3, 3
	v_readlane_b32 s6, v255, 52
	v_readlane_b32 s7, v255, 53
	s_add_u32 s4, s4, s6
	s_addc_u32 s5, s5, s7
	v_lshlrev_b32_e32 v0, 4, v194
	v_cmp_lt_i32_e32 vcc, v181, v180
	v_lshl_add_u64 v[68:69], s[4:5], 0, v[0:1]
	v_lshlrev_b32_e32 v66, 2, v194
	v_cndmask_b32_e32 v0, v169, v181, vcc
	v_cmp_lt_i32_e32 vcc, v182, v180
	v_lshlrev_b32_e32 v67, 2, v0
	v_or_b32_e32 v2, 0x100, v66
	v_cndmask_b32_e32 v0, v169, v182, vcc
	v_cmp_lt_i32_e32 vcc, v183, v180
	v_lshlrev_b32_e32 v92, 2, v0
	v_or_b32_e32 v4, 0x200, v66
	v_cndmask_b32_e32 v0, v169, v183, vcc
	v_cmp_lt_i32_e32 vcc, v192, v180
	v_lshlrev_b32_e32 v93, 2, v0
	s_add_u32 s11, s29, 0x3000
	v_cndmask_b32_e32 v0, v169, v192, vcc
	v_cmp_lt_i32_e32 vcc, v254, v180
	v_lshlrev_b32_e32 v94, 2, v0
	v_or_b32_e32 v6, 0x300, v66
	v_cndmask_b32_e32 v0, v169, v254, vcc
	v_cmp_lt_i32_e32 vcc, v186, v180
	v_lshlrev_b32_e32 v95, 2, v0
	s_addc_u32 s16, s94, 0
	v_cndmask_b32_e32 v0, v169, v186, vcc
	v_lshlrev_b32_e32 v96, 2, v0
	v_lshlrev_b32_e32 v0, 3, v194
	v_lshl_add_u64 v[70:71], s[60:61], 0, v[0:1]
	v_lshl_add_u64 v[72:73], s[58:59], 0, v[0:1]
	v_lshlrev_b32_e32 v0, 1, v2
	v_lshl_add_u64 v[74:75], s[60:61], 0, v[0:1]
	v_lshlrev_b32_e32 v0, 1, v4
	v_lshl_add_u64 v[76:77], s[60:61], 0, v[0:1]
	v_lshlrev_b32_e32 v0, 1, v6
	s_lshl_b32 s4, s2, 1
	s_mov_b32 s19, -1
	v_lshl_add_u64 v[78:79], s[60:61], 0, v[0:1]
	s_sub_i32 s17, 0x1000, s2
	s_sub_i32 s18, s4, 31
	s_lshl_b32 s3, s3, 4
	v_lshlrev_b32_e32 v0, 2, v2
	v_lshlrev_b32_e32 v97, 2, v4
	v_lshlrev_b32_e32 v98, 2, v6
	s_mov_b32 s101, 0x880f
	s_mov_b32 s99, 0
	s_cmp_eq_u32 s98, 2
	s_cbranch_scc0 .Lpn_nosplit
	s_and_b32 s4, s12, 31
	s_lshr_b32 s5, s12, 5
	s_cmp_lt_u32 s4, 8
	s_cbranch_scc0 .Lpn_classB
	s_mov_b64 s[6:7], exec
	v_readlane_b32 s8, v255, 3
	v_readlane_b32 s9, v255, 4
	s_and_b64 s[8:9], s[6:7], s[8:9]
	s_mov_b64 exec, s[8:9]
	s_cbranch_execz .Lpn_wdone_a
	s_lshl_b32 s5, s100, 3
	s_lshr_b32 s8, s12, 5
	s_lshl_b32 s8, s8, 2
	s_add_u32 s8, s14, s8
	s_addc_u32 s9, s15, 0
.Lpn_poll_a:
	global_load_dword v34, v1, s[8:9] offset:64 sc1
	s_waitcnt vmcnt(0)
	v_cmp_gt_u32_e32 vcc, s5, v34
	s_cbranch_vccz .Lpn_pdone_a
	s_sleep 2
	s_branch .Lpn_poll_a

; DI void norm_pair_phase(Frame& F, const float* srcL, const float* srcC, const float* g, const float* modl, int sub) {
;     ...
;     for (int task = gw; task < NT; task += NGW) {
;         int bi, r1, r2, j; bool single, isc = task >= NT_L;
;         if (!isc) { bi = task / 2049; j = task % 2049; single = (j == 0 || j == 2048); r1 = bi * SEQ + j; r2 = single ? r1 : bi * SEQ + SEQ - j; }
;         else { bi = 16; j = 0; single = false; r1 = TL + 2 * (task - NT_L); r2 = r1 + 1; }
;         if (bi != cur_bi) { cur_bi = bi; const float* mp = modl + (size_t)bi * MODW + sub * 3072;
; #pragma unroll
;             for (int q = 0; q < 4; ++q) { const int k = (lane + 64 * q) * 4; const f32x4 gg = *(const f32x4*)(g + k), sc = *(const f32x4*)(mp + 1024 + k); sh[q] = *(const f32x4*)(mp + k); gs[q] = gg * (sc + 1.0f); } }
;         const float* s1 = r1 < TL ? srcL + (size_t)r1 * DM : srcC + (size_t)(r1 - TL) * DM;
;         const float* s2 = r2 < TL ? srcL + (size_t)r2 * DM : srcC + (size_t)(r2 - TL) * DM;
;         f32x4 v1[4], v2[4]; float ss1 = 0.f, ss2 = 0.f;
; #pragma unroll
;         for (int q = 0; q < 4; ++q) { v1[q] = __builtin_nontemporal_load((const f32x4*)(s1 + (lane + 64 * q) * 4)); v2[q] = __builtin_nontemporal_load((const f32x4*)(s2 + (lane + 64 * q) * 4)); }
; #pragma unroll
;         for (int q = 0; q < 4; ++q) { ss1 += (v1[q][0] * v1[q][0] + v1[q][1] * v1[q][1]) + (v1[q][2] * v1[q][2] + v1[q][3] * v1[q][3]); ss2 += (v2[q][0] * v2[q][0] + v2[q][1] * v2[q][1]) + (v2[q][2] * v2[q][2] + v2[q][3] * v2[q][3]); }
; #pragma unroll
;         for (int o = 1; o < 64; o <<= 1) { ss1 += __shfl_xor(ss1, o); ss2 += __shfl_xor(ss2, o); }
;         const float rs1 = rsqrtf(ss1 * (1.0f / DM) + EPS), rs2 = rsqrtf(ss2 * (1.0f / DM) + EPS);
;         bf16_t* h1 = H + (size_t)r1 * DM; bf16_t* h2 = H + (size_t)r2 * DM;
;         bf16_t* hp = HS + (size_t)(isc ? r1 : bi * SEQ + j) * DM; bf16_t* hm = HS + (size_t)(isc ? r2 : bi * SEQ + 2048 + j) * DM;
; #pragma unroll
;         for (int q = 0; q < 4; ++q) {
;             const f32x4 o1 = v1[q] * rs1 * gs[q] + sh[q], o2 = v2[q] * rs2 * gs[q] + sh[q];
;             const int c = (lane + 64 * q) * 4;
;             u32x2 w; w.x = pk2(o1[0], o1[1]); w.y = pk2(o1[2], o1[3]); *(u32x2*)(h1 + c) = w;
;             if (!single) { u32x2 w2; w2.x = pk2(o2[0], o2[1]); w2.y = pk2(o2[2], o2[3]); *(u32x2*)(h2 + c) = w2; }
.Lpn_tail:
	s_cmp_eq_u32 s99, 1
	s_cbranch_scc0 .LBB0_578
	s_mov_b32 s99, 0
	s_mov_b64 s[6:7], exec
	v_readlane_b32 s8, v255, 3
	v_readlane_b32 s9, v255, 4
	s_and_b64 s[8:9], s[6:7], s[8:9]
	s_mov_b64 exec, s[8:9]
	s_cbranch_execz .Lpn_wdone_b
	s_lshl_b32 s5, s100, 3
	s_lshr_b32 s8, s12, 5
	s_lshl_b32 s8, s8, 2
	s_add_u32 s8, s14, s8
	s_addc_u32 s9, s15, 0

; DI void grid_barrier(unsigned* cnt, unsigned target) {
;     asm volatile("s_waitcnt vmcnt(0) lgkmcnt(0)" ::: "memory");
;     __syncthreads();
;     if (threadIdx.x == 0) {
;         __builtin_amdgcn_fence(__ATOMIC_RELEASE, "agent");
;         asm volatile("s_waitcnt vmcnt(0)" ::: "memory");
;         __hip_atomic_fetch_add(cnt, 1u, __ATOMIC_RELAXED, __HIP_MEMORY_SCOPE_AGENT);
;         while (__hip_atomic_load(cnt, __ATOMIC_RELAXED, __HIP_MEMORY_SCOPE_AGENT) < target) __builtin_amdgcn_s_sleep(2);
;         __builtin_amdgcn_fence(__ATOMIC_ACQUIRE, "agent");
;         asm volatile("s_waitcnt vmcnt(0)" ::: "memory");
;     }
;     __syncthreads();
; }
.LBB0_579:
	s_cmp_eq_u32 s98, 1
	s_cbranch_scc0 .Lcs_b_normal
	s_add_u32 s100, s100, 1
	s_mov_b32 s98, 2
	v_readlane_b32 s2, v255, 0
	s_cmp_lt_u32 s2, 64
	s_cbranch_scc0 .LBB0_585
	s_waitcnt vmcnt(0) lgkmcnt(0)
	s_barrier
	s_mov_b64 s[4:5], exec
	v_readlane_b32 s2, v255, 3
	v_readlane_b32 s3, v255, 4
	s_and_b64 s[2:3], s[4:5], s[2:3]
	s_mov_b64 exec, s[2:3]
	s_cbranch_execz .Lcs_b_arrdone
	buffer_wbl2 sc1
	s_waitcnt vmcnt(0)
	v_mov_b32_e32 v0, 1
	v_readlane_b32 s2, v255, 0
	s_and_b32 s2, s2, 7
	s_lshl_b32 s2, s2, 2
	s_add_u32 s2, s14, s2
	s_addc_u32 s3, s15, 0
	global_atomic_add v1, v0, s[2:3] offset:64

; DI void grid_barrier(unsigned* cnt, unsigned target) {
;     asm volatile("s_waitcnt vmcnt(0) lgkmcnt(0)" ::: "memory");
;     __syncthreads();
;     if (threadIdx.x == 0) {
;         __builtin_amdgcn_fence(__ATOMIC_RELEASE, "agent");
;         asm volatile("s_waitcnt vmcnt(0)" ::: "memory");
;         __hip_atomic_fetch_add(cnt, 1u, __ATOMIC_RELAXED, __HIP_MEMORY_SCOPE_AGENT);
;         while (__hip_atomic_load(cnt, __ATOMIC_RELAXED, __HIP_MEMORY_SCOPE_AGENT) < target) __builtin_amdgcn_s_sleep(2);
;         __builtin_amdgcn_fence(__ATOMIC_ACQUIRE, "agent");
;         asm volatile("s_waitcnt vmcnt(0)" ::: "memory");
;     }
;     __syncthreads();
; }
.Lch_start:
	s_waitcnt vmcnt(0) lgkmcnt(0)
	s_barrier
	v_readlane_b32 s10, v255, 61
	s_add_u32 s10, s10, 1
	s_nop 0
	v_writelane_b32 v255, s10, 61
	s_mov_b64 s[4:5], exec
	v_readlane_b32 s6, v255, 3
	v_readlane_b32 s7, v255, 4
	s_and_b64 s[6:7], s[4:5], s[6:7]
	s_mov_b64 exec, s[6:7]
	s_cbranch_execz .Lar_C
	buffer_wbl2 sc1
	s_waitcnt vmcnt(0)
	v_mov_b32_e32 v0, 1
	v_readlane_b32 s2, v255, 0
	s_bfe_u32 s2, s2, 0x20001
	s_lshl_b32 s2, s2, 2
	s_add_u32 s8, s14, s2
	s_addc_u32 s9, s15, 0
	global_atomic_add v1, v0, s[8:9] offset:160

; DI void grid_barrier(unsigned* cnt, unsigned target) {
;     asm volatile("s_waitcnt vmcnt(0) lgkmcnt(0)" ::: "memory");
;     __syncthreads();
;     if (threadIdx.x == 0) {
;         __builtin_amdgcn_fence(__ATOMIC_RELEASE, "agent");
;         asm volatile("s_waitcnt vmcnt(0)" ::: "memory");
;         __hip_atomic_fetch_add(cnt, 1u, __ATOMIC_RELAXED, __HIP_MEMORY_SCOPE_AGENT);
;         while (__hip_atomic_load(cnt, __ATOMIC_RELAXED, __HIP_MEMORY_SCOPE_AGENT) < target) __builtin_amdgcn_s_sleep(2);
;         __builtin_amdgcn_fence(__ATOMIC_ACQUIRE, "agent");
;         asm volatile("s_waitcnt vmcnt(0)" ::: "memory");
;     }
;     __syncthreads();
; }
.Lch_not2:
	s_cmp_eq_u32 s98, 3
	s_cbranch_scc0 .Lch_not3
	v_readlane_b32 s10, v255, 61
	s_lshl_b32 s10, s10, 6
	s_mov_b64 s[4:5], exec
	v_readlane_b32 s6, v255, 3
	v_readlane_b32 s7, v255, 4
	s_and_b64 s[6:7], s[4:5], s[6:7]
	s_mov_b64 exec, s[6:7]
	s_cbranch_execz .Lwd_C
	v_readlane_b32 s2, v255, 0
	s_bfe_u32 s2, s2, 0x20001
	s_lshl_b32 s2, s2, 2
	s_add_u32 s8, s14, s2
	s_addc_u32 s9, s15, 0
.Lwp_C:
	global_load_dword v0, v1, s[8:9] offset:160 sc1
	s_waitcnt vmcnt(0)
	v_cmp_gt_u32_e32 vcc, s10, v0
	s_cbranch_vccz .Lwi_C
	s_sleep 2
	s_branch .Lwp_C

; DI void grid_barrier(unsigned* cnt, unsigned target) {
;     asm volatile("s_waitcnt vmcnt(0) lgkmcnt(0)" ::: "memory");
;     __syncthreads();
;     if (threadIdx.x == 0) {
;         __builtin_amdgcn_fence(__ATOMIC_RELEASE, "agent");
;         asm volatile("s_waitcnt vmcnt(0)" ::: "memory");
;         __hip_atomic_fetch_add(cnt, 1u, __ATOMIC_RELAXED, __HIP_MEMORY_SCOPE_AGENT);
;         while (__hip_atomic_load(cnt, __ATOMIC_RELAXED, __HIP_MEMORY_SCOPE_AGENT) < target) __builtin_amdgcn_s_sleep(2);
;         __builtin_amdgcn_fence(__ATOMIC_ACQUIRE, "agent");
;         asm volatile("s_waitcnt vmcnt(0)" ::: "memory");
;     }
;     __syncthreads();
; }
.Lch_not3:
	s_cmp_eq_u32 s98, 4
	s_cbranch_scc0 .Lxl_pre
	s_waitcnt vmcnt(0) lgkmcnt(0)
	s_barrier
	v_readlane_b32 s10, v255, 62
	s_add_u32 s10, s10, 1
	s_nop 0
	v_writelane_b32 v255, s10, 62
	s_mov_b64 s[4:5], exec
	v_readlane_b32 s6, v255, 3
	v_readlane_b32 s7, v255, 4
	s_and_b64 s[6:7], s[4:5], s[6:7]
	s_mov_b64 exec, s[6:7]
	s_cbranch_execz .Lar_D
	buffer_wbl2 sc1
	s_waitcnt vmcnt(0)
	v_mov_b32_e32 v0, 1
	v_readlane_b32 s2, v255, 0
	s_bfe_u32 s2, s2, 0x20001
	s_lshl_b32 s2, s2, 2
	s_add_u32 s8, s14, s2
	s_addc_u32 s9, s15, 0
	global_atomic_add v1, v0, s[8:9] offset:176

; DI const float* in_ptr(const Args& AR, int i) { asm volatile("" : "+s"(i)); return GLOBAL_PTR(const float, AR.in[i]); }
; #define GRID_SYNC() do { nbar += (unsigned)gridDim.x; grid_barrier(barw, nbar); } while (0)
; __global__ void __launch_bounds__(512, 2) fwd_megakernel(Args args) {
;     ...
;             } else if (type == T_ATTE) {
;                 if (PM & 1024) { const float* qg_ = in_ptr(AR, 11) + li * 128; attn_even_lds(F, in_ptr(AR, 12) + (size_t)li * 12 * 465, qg_ + 64, qg_); attn_evenctx_lds(F, qg_ + 64, qg_); }
;             } else if (type == T_ATTO) {
;                 if (PM & 2048) { const float* qg_ = in_ptr(AR, 15) + li * 128; attn_odd_lds(F, qg_ + 64, qg_, l < 3); }
;             }
;             if (!(op == 4 || op == 6 || op == 7 || skip0)) GRID_SYNC();
.Lxl_pre:
	s_waitcnt lgkmcnt(0)
	s_cmp_eq_u32 s13, 0x100
	s_cbranch_scc0 .Lxl_no
	s_cmp_eq_u32 s44, 9
	s_cbranch_scc0 .Lat_not9
	s_waitcnt vmcnt(0) lgkmcnt(0)
	s_barrier
	v_readlane_b32 s10, v255, 63
	s_add_u32 s10, s10, 1
	s_nop 0
	v_writelane_b32 v255, s10, 63
	s_mov_b64 s[4:5], exec
	v_readlane_b32 s6, v255, 3
	v_readlane_b32 s7, v255, 4
	s_and_b64 s[6:7], s[4:5], s[6:7]
	s_mov_b64 exec, s[6:7]
	s_cbranch_execz .Lar_E
	buffer_wbl2 sc1
	s_waitcnt vmcnt(0)
	v_mov_b32_e32 v0, 1
	v_readlane_b32 s2, v255, 0
	s_and_b32 s2, s2, 7
	s_lshl_b32 s2, s2, 2
	s_add_u32 s8, s14, s2
	s_addc_u32 s9, s15, 0
	global_atomic_add v1, v0, s[8:9] offset:208
